# bar_last with all five GEMM loop heads 64-byte aligned (placement experiment)
# baseline (speedup 1.0000x reference)
; #define PG8_STAGE(bufoff, gbase, voff) do { _Pragma("unroll") for (int _i = 0; _i < 2; ++_i) \
;         __builtin_amdgcn_global_load_lds((const unsigned*)((const char*)(gbase) + (voff)[_i]), (LAS unsigned*)(lds + (bufoff) + ldsw + _i * 8192), 16, 0, 0); } while (0)
; #define PG8_WAIT_V(n) asm volatile("s_waitcnt vmcnt(" #n ")" ::: "memory")
; #define PG8_BAR __builtin_amdgcn_s_barrier()
; template <class Epi, class Sched>
; __device__ __forceinline__ void gemm_phase(LAS unsigned char* lds, const Gemm g, const Sched& S, const Epi& E) {
;     ...
;     const char* cA = (const char*)g.A + (size_t)cur.pm * tstepA + (size_t)cur.ka * 2; const char* cB = (const char*)g.Bt + (size_t)cur.pn * tstepB;
;     S.a_ready(cur);
;     PG8_STAGE(PG8_SB(0, 0), cB, voffB); PG8_STAGE(PG8_SB(0, 1), cB + hstepB, voffB); PG8_STAGE(PG8_SA(0, 0), cA, voffA); PG8_STAGE(PG8_SA(0, 1), cA + hstepA, voffA);
;     if (wr == 1) PG8_BAR;
;     PG8_WAIT_V(2); PG8_BAR;
;     PG8_STAGE(PG8_SB(1, 0), cB + kstep, voffB); PG8_STAGE(PG8_SA(1, 0), cA + kstep, voffA); PG8_STAGE(PG8_SB(1, 1), cB + hstepB + kstep, voffB);
;     PG8_WAIT_V(6); PG8_BAR;
;     for (;;) {
;         const bool has_next = S.next(ui + 1, nxt);
;         const char* nA = has_next ? (const char*)g.A + (size_t)nxt.pm * tstepA + (size_t)nxt.ka * 2 : cA; const char* nB = has_next ? (const char*)g.Bt + (size_t)nxt.pn * tstepB : cB;
;         for (int t = 0; t < nt; t += 2) {
.Lmy_rsfill_done:
	s_or_b64 exec, exec, s[100:101]
	s_mov_b32 s100, s54
	s_waitcnt lgkmcnt(0)
	s_barrier
	v_readlane_b32 s19, v253, 54
	s_branch .LBB0_134
	s_nop 0
	s_nop 0
	s_nop 0
	s_nop 0
	s_nop 0
	s_nop 0
	s_nop 0
.LBB0_132:
	s_mov_b64 s[26:27], 0

; #define PG8_STAGE(bufoff, gbase, voff) do { _Pragma("unroll") for (int _i = 0; _i < 2; ++_i) \
;         __builtin_amdgcn_global_load_lds((const unsigned*)((const char*)(gbase) + (voff)[_i]), (LAS unsigned*)(lds + (bufoff) + ldsw + _i * 8192), 16, 0, 0); } while (0)
; #define PG8_WAIT_V(n) asm volatile("s_waitcnt vmcnt(" #n ")" ::: "memory")
; #define PG8_BAR __builtin_amdgcn_s_barrier()
; template <class Epi, class Sched>
; __device__ __forceinline__ void gemm_phase(LAS unsigned char* lds, const Gemm g, const Sched& S, const Epi& E) {
;     ...
;     f32x4 acc[2][2][4][2];
; #pragma unroll
;     for (int a = 0; a < 2; ++a)
; #pragma unroll
;         for (int b = 0; b < 2; ++b)
; #pragma unroll
;             for (int m = 0; m < 4; ++m)
; #pragma unroll
;                 for (int n = 0; n < 2; ++n) acc[a][b][m][n] = (f32x4){0.f, 0.f, 0.f, 0.f};
;     bf16x8 At[4][2], B0[2][2], B1[2][2];
;     const char* cA = (const char*)g.A + (size_t)cur.pm * tstepA + (size_t)cur.ka * 2; const char* cB = (const char*)g.Bt + (size_t)cur.pn * tstepB;
;     S.a_ready(cur);
;     PG8_STAGE(PG8_SB(0, 0), cB, voffB); PG8_STAGE(PG8_SB(0, 1), cB + hstepB, voffB); PG8_STAGE(PG8_SA(0, 0), cA, voffA); PG8_STAGE(PG8_SA(0, 1), cA + hstepA, voffA);
;     if (wr == 1) PG8_BAR;
;     PG8_WAIT_V(2); PG8_BAR;
;     PG8_STAGE(PG8_SB(1, 0), cB + kstep, voffB); PG8_STAGE(PG8_SA(1, 0), cA + kstep, voffA); PG8_STAGE(PG8_SB(1, 1), cB + hstepB + kstep, voffB);
;     PG8_WAIT_V(6); PG8_BAR;
;     for (;;) {
;         const bool has_next = S.next(ui + 1, nxt);
;         const char* nA = has_next ? (const char*)g.A + (size_t)nxt.pm * tstepA + (size_t)nxt.ka * 2 : cA; const char* nB = has_next ? (const char*)g.Bt + (size_t)nxt.pn * tstepB : cB;
.LBB0_267:
	v_lshl_add_u64 v[14:15], s[24:25], 0, v[4:5]
	v_mov_b32_e32 v3, v5
	v_and_b32_e32 v142, 15, v143
	v_and_b32_e32 v22, 48, v143
	v_lshlrev_b32_e32 v23, 2, v143
	v_lshl_add_u64 v[16:17], s[24:25], 0, v[2:3]
	s_and_b32 s48, s44, 3
	v_lshl_or_b32 v22, v142, 6, v22
	s_lshl_b32 s4, s47, 13
	v_and_b32_e32 v23, 32, v23
	s_add_i32 m0, s50, 0x18000
	v_lshl_add_u64 v[14:15], v[14:15], 0, s[36:37]
	v_lshl_add_u64 v[18:19], s[20:21], 0, v[4:5]
	v_bitop3_b32 v24, v22, s4, v23 bitop3:0xde
	s_lshl_b32 s4, s48, 12
	s_waitcnt vmcnt(2)
	s_barrier
	global_load_lds_dwordx4 v[14:15], off
	v_lshl_add_u64 v[14:15], v[16:17], 0, s[36:37]
	s_add_i32 m0, s50, 0x1a000
	s_add_i32 s54, s50, 0x8000
	s_add_i32 s55, s50, 0xa000
	v_lshl_add_u64 v[20:21], s[20:21], 0, v[2:3]
	v_bitop3_b32 v144, v22, s4, v23 bitop3:0xde
	global_load_lds_dwordx4 v[14:15], off
	v_lshl_add_u64 v[14:15], v[18:19], 0, s[36:37]
	s_mov_b32 m0, s54
	s_add_u32 s4, s24, 0x158080
	global_load_lds_dwordx4 v[14:15], off
	v_lshl_add_u64 v[14:15], v[20:21], 0, s[36:37]
	s_mov_b32 m0, s55
	s_addc_u32 s5, s25, 0
	global_load_lds_dwordx4 v[14:15], off
	s_add_i32 m0, s50, 0x1c000
	v_lshl_add_u64 v[14:15], s[4:5], 0, v[4:5]
	global_load_lds_dwordx4 v[14:15], off
	v_lshl_add_u64 v[14:15], s[4:5], 0, v[2:3]
	s_add_i32 m0, s50, 0x1e000
	s_movk_i32 s10, 0x1580
	global_load_lds_dwordx4 v[14:15], off
	v_lshrrev_b32_e32 v11, 1, v11
	v_mul_lo_u32 v10, v10, s10
	s_mov_b32 s22, 0x15800
	v_mad_u64_u32 v[10:11], s[4:5], v11, s22, v[10:11]
	v_or_b32_e32 v10, v10, v12
	v_add_lshl_u32 v134, v10, v13, 1
	v_lshrrev_b32_e32 v10, 1, v6
	v_mul_lo_u32 v6, v7, s10
	v_mad_u64_u32 v[6:7], s[4:5], v10, s22, v[6:7]
	s_waitcnt vmcnt(6)
	v_or_b32_e32 v6, v6, v8
	s_cmpk_lt_u32 s45, 0x100
	v_add_lshl_u32 v136, v6, v9, 1
	v_mov_b32_e32 v6, 0
	v_readlane_b32 s4, v254, 13
	s_cselect_b64 s[18:19], -1, 0
	v_mov_b32_e32 v135, v5
	v_mov_b32_e32 v137, v5
	s_mov_b32 s59, 0
	v_add_u32_e32 v145, 0, v24
	s_mov_b32 s10, s4
	v_readlane_b32 s46, v253, 61
	v_mov_b32_e32 v7, v6
	v_mov_b32_e32 v8, v6
	v_mov_b32_e32 v9, v6
	v_mov_b32_e32 v10, v6
	v_mov_b32_e32 v11, v6
	v_mov_b32_e32 v12, v6
	v_mov_b32_e32 v13, v6
	v_mov_b32_e32 v14, v6
	v_mov_b32_e32 v15, v6
	v_mov_b32_e32 v16, v6
	v_mov_b32_e32 v17, v6
	v_mov_b32_e32 v18, v6
	v_mov_b32_e32 v19, v6
	v_mov_b32_e32 v20, v6
	v_mov_b32_e32 v21, v6
	v_mov_b32_e32 v22, v6
	v_mov_b32_e32 v23, v6
	v_mov_b32_e32 v24, v6
	v_mov_b32_e32 v25, v6
	v_mov_b32_e32 v30, v6
	v_mov_b32_e32 v31, v6
	v_mov_b32_e32 v32, v6
	v_mov_b32_e32 v33, v6
	v_mov_b32_e32 v38, v6
	v_mov_b32_e32 v39, v6
	v_mov_b32_e32 v40, v6
	v_mov_b32_e32 v41, v6
	v_mov_b32_e32 v46, v6
	v_mov_b32_e32 v47, v6
	v_mov_b32_e32 v48, v6
	v_mov_b32_e32 v49, v6
	v_mov_b32_e32 v26, v6
	v_mov_b32_e32 v27, v6
	v_mov_b32_e32 v28, v6
	v_mov_b32_e32 v29, v6
	v_mov_b32_e32 v34, v6
	v_mov_b32_e32 v35, v6
	v_mov_b32_e32 v36, v6
	v_mov_b32_e32 v37, v6
	v_mov_b32_e32 v42, v6
	v_mov_b32_e32 v43, v6
	v_mov_b32_e32 v44, v6
	v_mov_b32_e32 v45, v6
	v_mov_b32_e32 v50, v6
	v_mov_b32_e32 v51, v6
	v_mov_b32_e32 v52, v6
	v_mov_b32_e32 v53, v6
	v_mov_b32_e32 v54, v6
	v_mov_b32_e32 v55, v6
	v_mov_b32_e32 v56, v6
	v_mov_b32_e32 v57, v6
	v_mov_b32_e32 v58, v6
	v_mov_b32_e32 v59, v6
	v_mov_b32_e32 v60, v6
	v_mov_b32_e32 v61, v6
	v_mov_b32_e32 v62, v6
	v_mov_b32_e32 v63, v6
	v_mov_b32_e32 v64, v6
	v_mov_b32_e32 v65, v6
	v_mov_b32_e32 v66, v6
	v_mov_b32_e32 v67, v6
	v_mov_b32_e32 v68, v6
	v_mov_b32_e32 v69, v6
	v_mov_b32_e32 v70, v6
	v_mov_b32_e32 v71, v6
	v_mov_b32_e32 v72, v6
	v_mov_b32_e32 v73, v6
	v_mov_b32_e32 v74, v6
	v_mov_b32_e32 v75, v6
	v_mov_b32_e32 v76, v6
	v_mov_b32_e32 v77, v6
	v_mov_b32_e32 v78, v6
	v_mov_b32_e32 v79, v6
	v_mov_b32_e32 v80, v6
	v_mov_b32_e32 v81, v6
	v_mov_b32_e32 v82, v6
	v_mov_b32_e32 v83, v6
	v_mov_b32_e32 v84, v6
	v_mov_b32_e32 v85, v6
	v_mov_b32_e32 v86, v6
	v_mov_b32_e32 v87, v6
	v_mov_b32_e32 v88, v6
	v_mov_b32_e32 v89, v6
	v_mov_b32_e32 v94, v6
	v_mov_b32_e32 v95, v6
	v_mov_b32_e32 v96, v6
	v_mov_b32_e32 v97, v6
	v_mov_b32_e32 v102, v6
	v_mov_b32_e32 v103, v6
	v_mov_b32_e32 v104, v6
	v_mov_b32_e32 v105, v6
	v_mov_b32_e32 v114, v6
	v_mov_b32_e32 v115, v6
	v_mov_b32_e32 v116, v6
	v_mov_b32_e32 v117, v6
	v_mov_b32_e32 v90, v6
	v_mov_b32_e32 v91, v6
	v_mov_b32_e32 v92, v6
	v_mov_b32_e32 v93, v6
	v_mov_b32_e32 v98, v6
	v_mov_b32_e32 v99, v6
	v_mov_b32_e32 v100, v6
	v_mov_b32_e32 v101, v6
	v_mov_b32_e32 v106, v6
	v_mov_b32_e32 v107, v6
	v_mov_b32_e32 v108, v6
	v_mov_b32_e32 v109, v6
	v_mov_b32_e32 v110, v6
	v_mov_b32_e32 v111, v6
	v_mov_b32_e32 v112, v6
	v_mov_b32_e32 v113, v6
	v_mov_b32_e32 v118, v6
	v_mov_b32_e32 v119, v6
	v_mov_b32_e32 v120, v6
	v_mov_b32_e32 v121, v6
	v_mov_b32_e32 v122, v6
	v_mov_b32_e32 v123, v6
	v_mov_b32_e32 v124, v6
	v_mov_b32_e32 v125, v6
	v_mov_b32_e32 v126, v6
	v_mov_b32_e32 v127, v6
	v_mov_b32_e32 v128, v6
	v_mov_b32_e32 v129, v6
	v_mov_b32_e32 v130, v6
	v_mov_b32_e32 v131, v6
	v_mov_b32_e32 v132, v6
	v_mov_b32_e32 v133, v6
	s_barrier
	s_branch .LBB0_270
	s_nop 0
	s_nop 0
	s_nop 0
	s_nop 0
	s_nop 0
	s_nop 0
	s_nop 0
	s_nop 0
	s_nop 0
	s_nop 0
	s_nop 0
	s_nop 0
	s_nop 0
.LBB0_268:
	s_mov_b64 s[22:23], s[24:25]
	s_mov_b64 s[4:5], s[20:21]
	s_mov_b32 s58, s59
	s_andn2_b64 vcc, exec, s[38:39]
	s_cbranch_vccz .LBB0_288

; #define PG8_STAGE(bufoff, gbase, voff) do { _Pragma("unroll") for (int _i = 0; _i < 2; ++_i) \
;         __builtin_amdgcn_global_load_lds((const unsigned*)((const char*)(gbase) + (voff)[_i]), (LAS unsigned*)(lds + (bufoff) + ldsw + _i * 8192), 16, 0, 0); } while (0)
; #define PG8_WAIT_V(n) asm volatile("s_waitcnt vmcnt(" #n ")" ::: "memory")
; #define PG8_BAR __builtin_amdgcn_s_barrier()
; template <class Epi, class Sched>
; __device__ __forceinline__ void gemm_phase(LAS unsigned char* lds, const Gemm g, const Sched& S, const Epi& E) {
;     ...
;     const char* cA = (const char*)g.A + (size_t)cur.pm * tstepA + (size_t)cur.ka * 2; const char* cB = (const char*)g.Bt + (size_t)cur.pn * tstepB;
;     S.a_ready(cur);
;     PG8_STAGE(PG8_SB(0, 0), cB, voffB); PG8_STAGE(PG8_SB(0, 1), cB + hstepB, voffB); PG8_STAGE(PG8_SA(0, 0), cA, voffA); PG8_STAGE(PG8_SA(0, 1), cA + hstepA, voffA);
;     if (wr == 1) PG8_BAR;
;     PG8_WAIT_V(2); PG8_BAR;
;     PG8_STAGE(PG8_SB(1, 0), cB + kstep, voffB); PG8_STAGE(PG8_SA(1, 0), cA + kstep, voffA); PG8_STAGE(PG8_SB(1, 1), cB + hstepB + kstep, voffB);
;     PG8_WAIT_V(6); PG8_BAR;
;     for (;;) {
;         const bool has_next = S.next(ui + 1, nxt);
;         const char* nA = has_next ? (const char*)g.A + (size_t)nxt.pm * tstepA + (size_t)nxt.ka * 2 : cA; const char* nB = has_next ? (const char*)g.Bt + (size_t)nxt.pn * tstepB : cB;
.LBB0_649:
	s_add_u32 s8, s14, 0xd000000
	v_lshrrev_b32_e32 v20, 1, v4
	s_addc_u32 s9, s15, 0
	v_and_b32_e32 v189, 15, v4
	v_and_b32_e32 v21, 24, v20
	s_add_u32 s10, s14, 0x100000
	v_lshlrev_b32_e32 v20, 1, v21
	v_lshlrev_b32_e32 v22, 6, v189
	v_lshlrev_b32_e32 v4, 2, v4
	s_addc_u32 s11, s15, 0
	s_and_b32 s18, s13, 3
	v_or_b32_e32 v23, v22, v20
	s_lshl_b32 s13, s16, 13
	v_and_b32_e32 v4, 32, v4
	s_add_i32 m0, s47, 0x18000
	v_lshl_add_u64 v[12:13], v[12:13], 0, s[36:37]
	s_lshl_b32 s51, s16, 6
	v_bitop3_b32 v24, v23, s13, v4 bitop3:0xde
	s_lshl_b32 s13, s18, 12
	s_waitcnt vmcnt(2)
	s_barrier
	global_load_lds_dwordx4 v[12:13], off
	v_lshl_add_u64 v[10:11], v[10:11], 0, s[36:37]
	s_add_i32 m0, s47, 0x1a000
	s_add_i32 s52, s47, 0x8000
	s_add_i32 s53, s47, 0xa000
	global_load_lds_dwordx4 v[10:11], off
	v_lshl_add_u64 v[6:7], v[6:7], 0, s[36:37]
	s_mov_b32 m0, s52
	s_add_u32 s16, s28, 0x80080
	global_load_lds_dwordx4 v[6:7], off
	v_lshl_add_u64 v[6:7], v[8:9], 0, s[36:37]
	s_mov_b32 m0, s53
	s_addc_u32 s17, s29, 0
	global_load_lds_dwordx4 v[6:7], off
	s_add_i32 m0, s47, 0x1c000
	v_lshl_add_u64 v[6:7], s[16:17], 0, v[182:183]
	global_load_lds_dwordx4 v[6:7], off
	v_lshl_add_u64 v[6:7], s[16:17], 0, v[186:187]
	s_add_i32 m0, s47, 0x1e000
	v_lshl_or_b32 v188, s18, 5, v21
	global_load_lds_dwordx4 v[6:7], off
	v_bitop3_b32 v231, v23, s13, v4 bitop3:0xde
	v_lshlrev_b32_e32 v4, 2, v188
	v_lshl_add_u64 v[6:7], s[14:15], 0, v[4:5]
	s_mov_b64 s[16:17], 0x200000
	s_cmpk_lt_u32 s12, 0x100
	v_lshl_add_u64 v[190:191], v[6:7], 0, s[16:17]
	s_mov_b64 s[16:17], 0x600000
	s_cselect_b64 s[12:13], -1, 0
	v_lshl_add_u64 v[192:193], v[6:7], 0, s[16:17]
	s_lshl_b32 s16, s18, 10
	s_add_u32 s14, s14, s16
	s_addc_u32 s15, s15, 0
	v_mov_b32_e32 v23, v5
	v_lshl_add_u64 v[6:7], s[14:15], 0, v[22:23]
	v_mov_b32_e32 v21, v5
	v_lshlrev_b32_e32 v4, 15, v14
	v_lshl_add_u64 v[6:7], v[6:7], 0, v[20:21]
	s_mov_b64 s[14:15], 0x5000000
	v_and_b32_e32 v4, 0xffff0000, v4
	v_lshl_add_u64 v[194:195], v[6:7], 0, s[14:15]
	v_lshl_add_u32 v4, v15, 12, v4
	v_and_b32_e32 v6, 1, v14
	v_lshl_or_b32 v4, v6, 6, v4
	v_lshl_add_u32 v196, v16, 1, v4
	v_lshlrev_b32_e32 v4, 15, v17
	v_and_b32_e32 v4, 0xffff0000, v4
	s_waitcnt vmcnt(6)
	v_lshl_add_u32 v4, v18, 12, v4
	v_and_b32_e32 v6, 1, v17
	v_lshl_or_b32 v4, v6, 6, v4
	v_mov_b32_e32 v197, v5
	v_lshl_add_u32 v212, v19, 1, v4
	v_mov_b32_e32 v213, v5
	s_mov_b32 s54, 0
	v_add_u32_e32 v235, 0, v24
	s_barrier
	s_branch .LBB0_652
	s_nop 0
	s_nop 0
	s_nop 0
	s_nop 0
	s_nop 0
	s_nop 0
	s_nop 0
	s_nop 0
	s_nop 0
	s_nop 0
	s_nop 0
	s_nop 0
	s_nop 0
	s_nop 0
.LBB0_650:
	s_mov_b64 s[22:23], 0

; #define PG8_STAGE(bufoff, gbase, voff) do { _Pragma("unroll") for (int _i = 0; _i < 2; ++_i) \
;         __builtin_amdgcn_global_load_lds((const unsigned*)((const char*)(gbase) + (voff)[_i]), (LAS unsigned*)(lds + (bufoff) + ldsw + _i * 8192), 16, 0, 0); } while (0)
; #define PG8_WAIT_V(n) asm volatile("s_waitcnt vmcnt(" #n ")" ::: "memory")
; #define PG8_BAR __builtin_amdgcn_s_barrier()
; template <class Epi, class Sched>
; __device__ __forceinline__ void gemm_phase(LAS unsigned char* lds, const Gemm g, const Sched& S, const Epi& E) {
;     ...
;     f32x4 acc[2][2][4][2];
; #pragma unroll
;     for (int a = 0; a < 2; ++a)
; #pragma unroll
;         for (int b = 0; b < 2; ++b)
; #pragma unroll
;             for (int m = 0; m < 4; ++m)
; #pragma unroll
;                 for (int n = 0; n < 2; ++n) acc[a][b][m][n] = (f32x4){0.f, 0.f, 0.f, 0.f};
;     bf16x8 At[4][2], B0[2][2], B1[2][2];
;     const char* cA = (const char*)g.A + (size_t)cur.pm * tstepA + (size_t)cur.ka * 2; const char* cB = (const char*)g.Bt + (size_t)cur.pn * tstepB;
;     S.a_ready(cur);
;     PG8_STAGE(PG8_SB(0, 0), cB, voffB); PG8_STAGE(PG8_SB(0, 1), cB + hstepB, voffB); PG8_STAGE(PG8_SA(0, 0), cA, voffA); PG8_STAGE(PG8_SA(0, 1), cA + hstepA, voffA);
;     if (wr == 1) PG8_BAR;
;     PG8_WAIT_V(2); PG8_BAR;
;     PG8_STAGE(PG8_SB(1, 0), cB + kstep, voffB); PG8_STAGE(PG8_SA(1, 0), cA + kstep, voffA); PG8_STAGE(PG8_SB(1, 1), cB + hstepB + kstep, voffB);
;     PG8_WAIT_V(6); PG8_BAR;
;     ...
;         for (int a = 0; a < 2; ++a)
; #pragma unroll
;             for (int b = 0; b < 2; ++b)
; #pragma unroll
;                 for (int m = 0; m < 4; ++m)
; #pragma unroll
;                     for (int n = 0; n < 2; ++n) acc[a][b][m][n] = (f32x4){0.f, 0.f, 0.f, 0.f};
;         cur = nxt; cA = nA; cB = nB; ++ui;
.LBB0_995:
	v_mov_b32_e32 v139, v5
	v_lshl_add_u64 v[10:11], s[24:25], 0, v[138:139]
	v_mov_b32_e32 v135, v5
	v_lshl_add_u64 v[12:13], s[24:25], 0, v[134:135]
	v_mov_b32_e32 v141, v5
	s_add_i32 m0, s58, 0x18000
	v_lshl_add_u64 v[10:11], v[10:11], 0, s[36:37]
	v_lshl_add_u64 v[18:19], s[26:27], 0, v[140:141]
	v_mov_b32_e32 v137, v5
	s_waitcnt vmcnt(2)
	s_barrier
	global_load_lds_dwordx4 v[10:11], off
	v_lshl_add_u64 v[10:11], v[12:13], 0, s[36:37]
	s_add_i32 m0, s58, 0x1a000
	s_add_i32 s62, s58, 0x8000
	v_lshl_add_u64 v[20:21], s[26:27], 0, v[136:137]
	global_load_lds_dwordx4 v[10:11], off
	v_lshl_add_u64 v[10:11], v[18:19], 0, s[36:37]
	s_mov_b32 m0, s62
	s_add_i32 s63, s58, 0xa000
	v_lshl_add_u64 v[14:15], s[4:5], 0, v[138:139]
	global_load_lds_dwordx4 v[10:11], off
	v_lshl_add_u64 v[10:11], v[20:21], 0, s[36:37]
	s_mov_b32 m0, s63
	v_lshl_add_u64 v[16:17], s[4:5], 0, v[134:135]
	global_load_lds_dwordx4 v[10:11], off
	s_add_i32 m0, s58, 0x1c000
	v_lshl_add_u64 v[10:11], v[14:15], 0, s[36:37]
	global_load_lds_dwordx4 v[10:11], off
	v_lshl_add_u64 v[10:11], v[16:17], 0, s[36:37]
	s_add_i32 m0, s58, 0x1e000
	v_and_b32_e32 v168, 15, v169
	global_load_lds_dwordx4 v[10:11], off
	v_and_b32_e32 v9, 48, v169
	v_lshlrev_b32_e32 v10, 2, v169
	s_and_b32 s54, s50, 3
	s_lshr_b32 s64, s6, 6
	v_lshl_or_b32 v9, v168, 6, v9
	s_lshl_b32 s4, s52, 13
	v_and_b32_e32 v10, 32, v10
	v_bitop3_b32 v11, v9, s4, v10 bitop3:0xde
	s_lshl_b32 s4, s54, 12
	s_add_i32 s65, s64, -2
	s_cmpk_lt_u32 s51, 0x100
	v_bitop3_b32 v148, v9, s4, v10 bitop3:0xde
	s_cselect_b64 s[28:29], -1, 0
	s_add_u32 s4, s34, 0x80
	v_add_u32_e32 v4, v8, v4
	s_addc_u32 s5, 0, 0
	v_add_lshl_u32 v4, v4, v7, 1
	v_add_u32_e32 v2, v6, v2
	v_lshl_add_u64 v[142:143], s[4:5], 0, v[4:5]
	v_add_lshl_u32 v4, v2, v3, 1
	s_waitcnt vmcnt(6)
	v_lshl_add_u64 v[144:145], s[4:5], 0, v[4:5]
	v_mov_b32_e32 v4, v5
	v_mov_b32_e32 v2, v5
	v_mov_b32_e32 v3, v5
	v_add_u32_e32 v149, 0, v11
	v_mov_b64_e32 v[8:9], v[4:5]
	v_mov_b64_e32 v[12:13], v[4:5]
	v_mov_b64_e32 v[16:17], v[4:5]
	v_mov_b64_e32 v[20:21], v[4:5]
	v_mov_b64_e32 v[24:25], v[4:5]
	v_mov_b64_e32 v[32:33], v[4:5]
	v_mov_b64_e32 v[40:41], v[4:5]
	v_mov_b64_e32 v[48:49], v[4:5]
	v_mov_b64_e32 v[28:29], v[4:5]
	v_mov_b64_e32 v[36:37], v[4:5]
	v_mov_b64_e32 v[44:45], v[4:5]
	v_mov_b64_e32 v[52:53], v[4:5]
	v_mov_b64_e32 v[56:57], v[4:5]
	v_mov_b64_e32 v[60:61], v[4:5]
	v_mov_b64_e32 v[64:65], v[4:5]
	v_mov_b64_e32 v[68:69], v[4:5]
	v_mov_b64_e32 v[72:73], v[4:5]
	v_mov_b64_e32 v[76:77], v[4:5]
	v_mov_b64_e32 v[80:81], v[4:5]
	v_mov_b64_e32 v[84:85], v[4:5]
	v_mov_b64_e32 v[88:89], v[4:5]
	v_mov_b64_e32 v[96:97], v[4:5]
	v_mov_b64_e32 v[104:105], v[4:5]
	v_mov_b64_e32 v[116:117], v[4:5]
	v_mov_b64_e32 v[92:93], v[4:5]
	v_mov_b64_e32 v[100:101], v[4:5]
	v_mov_b64_e32 v[108:109], v[4:5]
	v_mov_b64_e32 v[112:113], v[4:5]
	v_mov_b64_e32 v[120:121], v[4:5]
	v_mov_b64_e32 v[124:125], v[4:5]
	v_mov_b64_e32 v[128:129], v[4:5]
	v_mov_b64_e32 v[132:133], v[4:5]
	v_readlane_b32 s4, v254, 13
	s_mov_b32 s66, 0
	v_mov_b64_e32 v[6:7], v[2:3]
	v_mov_b64_e32 v[10:11], v[2:3]
	v_mov_b64_e32 v[14:15], v[2:3]
	v_mov_b64_e32 v[18:19], v[2:3]
	v_mov_b64_e32 v[22:23], v[2:3]
	v_mov_b64_e32 v[30:31], v[2:3]
	v_mov_b64_e32 v[38:39], v[2:3]
	v_mov_b64_e32 v[46:47], v[2:3]
	v_mov_b64_e32 v[26:27], v[2:3]
	v_mov_b64_e32 v[34:35], v[2:3]
	v_mov_b64_e32 v[42:43], v[2:3]
	v_mov_b64_e32 v[50:51], v[2:3]
	v_mov_b64_e32 v[54:55], v[2:3]
	v_mov_b64_e32 v[58:59], v[2:3]
	v_mov_b64_e32 v[62:63], v[2:3]
	v_mov_b64_e32 v[66:67], v[2:3]
	v_mov_b64_e32 v[70:71], v[2:3]
	v_mov_b64_e32 v[74:75], v[2:3]
	v_mov_b64_e32 v[78:79], v[2:3]
	v_mov_b64_e32 v[82:83], v[2:3]
	v_mov_b64_e32 v[86:87], v[2:3]
	v_mov_b64_e32 v[94:95], v[2:3]
	v_mov_b64_e32 v[102:103], v[2:3]
	v_mov_b64_e32 v[114:115], v[2:3]
	v_mov_b64_e32 v[90:91], v[2:3]
	v_mov_b64_e32 v[98:99], v[2:3]
	v_mov_b64_e32 v[106:107], v[2:3]
	v_mov_b64_e32 v[110:111], v[2:3]
	v_mov_b64_e32 v[118:119], v[2:3]
	v_mov_b64_e32 v[122:123], v[2:3]
	v_mov_b64_e32 v[126:127], v[2:3]
	v_mov_b64_e32 v[130:131], v[2:3]
	s_mov_b32 s6, s4
	v_readlane_b32 s53, v253, 61
	s_barrier
	s_branch .LBB0_998
	s_nop 0
	s_nop 0
	s_nop 0
	s_nop 0
	s_nop 0
	s_nop 0
	s_nop 0
	s_nop 0
.LBB0_996:
	v_mov_b32_e32 v4, v5
	v_mov_b32_e32 v2, v5
	v_mov_b32_e32 v3, v5
	v_mov_b64_e32 v[8:9], v[4:5]
	v_mov_b64_e32 v[12:13], v[4:5]
	v_mov_b64_e32 v[16:17], v[4:5]
	v_mov_b64_e32 v[20:21], v[4:5]
	v_mov_b64_e32 v[24:25], v[4:5]
	v_mov_b64_e32 v[32:33], v[4:5]
	v_mov_b64_e32 v[40:41], v[4:5]
	v_mov_b64_e32 v[48:49], v[4:5]
	v_mov_b64_e32 v[28:29], v[4:5]
	v_mov_b64_e32 v[36:37], v[4:5]
	v_mov_b64_e32 v[44:45], v[4:5]
	v_mov_b64_e32 v[52:53], v[4:5]
	v_mov_b64_e32 v[56:57], v[4:5]
	v_mov_b64_e32 v[60:61], v[4:5]
	v_mov_b64_e32 v[64:65], v[4:5]
	v_mov_b64_e32 v[68:69], v[4:5]
	v_mov_b64_e32 v[72:73], v[4:5]
	v_mov_b64_e32 v[76:77], v[4:5]
	v_mov_b64_e32 v[80:81], v[4:5]
	v_mov_b64_e32 v[84:85], v[4:5]
	v_mov_b64_e32 v[88:89], v[4:5]
	v_mov_b64_e32 v[96:97], v[4:5]
	v_mov_b64_e32 v[104:105], v[4:5]
	v_mov_b64_e32 v[116:117], v[4:5]
	v_mov_b64_e32 v[92:93], v[4:5]
	v_mov_b64_e32 v[100:101], v[4:5]
	v_mov_b64_e32 v[108:109], v[4:5]
	v_mov_b64_e32 v[112:113], v[4:5]
	v_mov_b64_e32 v[120:121], v[4:5]
	v_mov_b64_e32 v[124:125], v[4:5]
	v_mov_b64_e32 v[128:129], v[4:5]
	v_mov_b64_e32 v[132:133], v[4:5]
	v_mov_b64_e32 v[6:7], v[2:3]
	v_mov_b64_e32 v[10:11], v[2:3]
	v_mov_b64_e32 v[14:15], v[2:3]
	v_mov_b64_e32 v[18:19], v[2:3]
	v_mov_b64_e32 v[22:23], v[2:3]
	v_mov_b64_e32 v[30:31], v[2:3]
	v_mov_b64_e32 v[38:39], v[2:3]
	v_mov_b64_e32 v[46:47], v[2:3]
	v_mov_b64_e32 v[26:27], v[2:3]
	v_mov_b64_e32 v[34:35], v[2:3]
	v_mov_b64_e32 v[42:43], v[2:3]
	v_mov_b64_e32 v[50:51], v[2:3]
	v_mov_b64_e32 v[54:55], v[2:3]
	v_mov_b64_e32 v[58:59], v[2:3]
	v_mov_b64_e32 v[62:63], v[2:3]
	v_mov_b64_e32 v[66:67], v[2:3]
	v_mov_b64_e32 v[70:71], v[2:3]
	v_mov_b64_e32 v[74:75], v[2:3]
	v_mov_b64_e32 v[78:79], v[2:3]
	v_mov_b64_e32 v[82:83], v[2:3]
	v_mov_b64_e32 v[86:87], v[2:3]
	v_mov_b64_e32 v[94:95], v[2:3]
	v_mov_b64_e32 v[102:103], v[2:3]
	v_mov_b64_e32 v[114:115], v[2:3]
	v_mov_b64_e32 v[90:91], v[2:3]
	v_mov_b64_e32 v[98:99], v[2:3]
	v_mov_b64_e32 v[106:107], v[2:3]
	v_mov_b64_e32 v[110:111], v[2:3]
	v_mov_b64_e32 v[118:119], v[2:3]
	v_mov_b64_e32 v[122:123], v[2:3]
	v_mov_b64_e32 v[126:127], v[2:3]
	v_mov_b64_e32 v[130:131], v[2:3]
	s_mov_b32 s6, s67
	s_mov_b32 s53, s68
	s_mov_b64 s[24:25], s[44:45]
	s_mov_b64 s[26:27], s[4:5]
	s_mov_b32 s66, s69
